# combined + GEMM K-loops: first iteration peeled with srcC=0 (no 128-v_mov accumulator zeroing per tile)
# speedup vs baseline: 1.0148x; 1.0133x over previous
.LBB0_255:
	s_ashr_i32 s15, s14, 31
	s_lshl_b64 s[20:21], s[14:15], 19
	s_add_u32 s42, s31, s20
	s_addc_u32 s43, s34, s21
	s_and_b64 s[20:21], s[4:5], exec
	s_cselect_b32 s15, s43, s53
	s_cselect_b32 s20, s42, s52
	s_ashr_i32 s13, s12, 31
	s_lshl_b64 s[50:51], s[12:13], 19
	s_add_u32 s50, s35, s50
	s_addc_u32 s51, s36, s51
	s_and_b64 s[58:59], s[4:5], exec
	s_cselect_b32 s13, s51, s57
	s_cselect_b32 s21, s50, s56
	s_add_u32 s52, s52, 0x40080
	s_addc_u32 s53, s53, 0
	s_add_u32 s73, s56, 0x100
	s_addc_u32 s75, s57, 0
	s_mov_b32 s82, -2
	s_add_u32 s0, s52, 0xfffc0080
	s_addc_u32 s56, s53, -1
	s_add_i32 s83, 0, 0x10000
	s_cmp_eq_u32 s82, 12
	s_cselect_b32 s59, s15, s56
	s_cselect_b32 s58, s20, s0
	s_cselect_b32 s57, s13, s75
	s_cselect_b32 s56, s21, s73
	s_add_i32 s0, 0, 0x14000
	v_add_u32_e32 v94, s83, v171
	v_add_u32_e32 v155, s0, v171
	ds_read_b128 v[74:77], v94
	ds_read_b128 v[78:81], v94 offset:1024
	ds_read_b128 v[90:93], v94 offset:2048
	ds_read_b128 v[94:97], v94 offset:3072
	ds_read_b128 v[180:183], v155
	ds_read_b128 v[184:187], v155 offset:1024
	ds_read_b128 v[188:191], v155 offset:2048
	ds_read_b128 v[192:195], v155 offset:3072
	v_lshl_add_u64 v[168:169], s[52:53], 0, v[164:165]
	s_add_i32 m0, s61, 0xc000
	ds_read_b128 v[196:199], v177
	ds_read_b128 v[200:203], v177 offset:1024
	ds_read_b128 v[204:207], v177 offset:2048
	ds_read_b128 v[208:211], v177 offset:3072
	ds_read_b128 v[212:215], v177 offset:4096
	ds_read_b128 v[216:219], v177 offset:5120
	ds_read_b128 v[230:233], v177 offset:6144
	ds_read_b128 v[238:241], v177 offset:7168
	global_load_lds_dwordx4 v[168:169], off
	v_lshl_add_u64 v[168:169], s[52:53], 0, v[166:167]
	s_add_i32 m0, s61, 0xe000
	s_nop 0
	global_load_lds_dwordx4 v[168:169], off
	s_waitcnt vmcnt(8)
	s_waitcnt lgkmcnt(0)
	s_barrier
	s_setprio 1
	s_waitcnt lgkmcnt(0)
	v_mfma_f32_16x16x32_bf16 v[142:145], v[74:77], v[196:199], 0
	v_mfma_f32_16x16x32_bf16 v[134:137], v[90:93], v[196:199], 0
	v_mfma_f32_16x16x32_bf16 v[126:129], v[74:77], v[204:207], 0
	v_mfma_f32_16x16x32_bf16 v[118:121], v[90:93], v[204:207], 0
	v_mfma_f32_16x16x32_bf16 v[110:113], v[74:77], v[212:215], 0
	v_mfma_f32_16x16x32_bf16 v[102:105], v[90:93], v[212:215], 0
	v_mfma_f32_16x16x32_bf16 v[86:89], v[74:77], v[230:233], 0
	v_mfma_f32_16x16x32_bf16 v[70:73], v[90:93], v[230:233], 0
	v_mfma_f32_16x16x32_bf16 v[142:145], v[78:81], v[200:203], v[142:145]
	v_mfma_f32_16x16x32_bf16 v[134:137], v[94:97], v[200:203], v[134:137]
	v_mfma_f32_16x16x32_bf16 v[126:129], v[78:81], v[208:211], v[126:129]
	v_mfma_f32_16x16x32_bf16 v[118:121], v[94:97], v[208:211], v[118:121]
	v_mfma_f32_16x16x32_bf16 v[110:113], v[78:81], v[216:219], v[110:113]
	v_mfma_f32_16x16x32_bf16 v[102:105], v[94:97], v[216:219], v[102:105]
	v_mfma_f32_16x16x32_bf16 v[86:89], v[78:81], v[238:241], v[86:89]
	v_mfma_f32_16x16x32_bf16 v[70:73], v[94:97], v[238:241], v[70:73]
	s_setprio 0
	s_setprio 1
	v_mfma_f32_16x16x32_bf16 v[138:141], v[180:183], v[196:199], 0
	v_mfma_f32_16x16x32_bf16 v[130:133], v[188:191], v[196:199], 0
	v_mfma_f32_16x16x32_bf16 v[122:125], v[180:183], v[204:207], 0
	v_mfma_f32_16x16x32_bf16 v[114:117], v[188:191], v[204:207], 0
	v_mfma_f32_16x16x32_bf16 v[106:109], v[180:183], v[212:215], 0
	v_mfma_f32_16x16x32_bf16 v[98:101], v[188:191], v[212:215], 0
	v_mfma_f32_16x16x32_bf16 v[82:85], v[180:183], v[230:233], 0
	v_mfma_f32_16x16x32_bf16 v[66:69], v[188:191], v[230:233], 0
	v_mfma_f32_16x16x32_bf16 v[138:141], v[184:187], v[200:203], v[138:141]
	v_mfma_f32_16x16x32_bf16 v[130:133], v[192:195], v[200:203], v[130:133]
	v_mfma_f32_16x16x32_bf16 v[122:125], v[184:187], v[208:211], v[122:125]
	v_mfma_f32_16x16x32_bf16 v[114:117], v[192:195], v[208:211], v[114:117]
	v_mfma_f32_16x16x32_bf16 v[106:109], v[184:187], v[216:219], v[106:109]
	v_mfma_f32_16x16x32_bf16 v[98:101], v[192:195], v[216:219], v[98:101]
	v_mfma_f32_16x16x32_bf16 v[82:85], v[184:187], v[238:241], v[82:85]
	v_mfma_f32_16x16x32_bf16 v[66:69], v[192:195], v[238:241], v[66:69]
	s_setprio 0
	s_barrier
	s_add_i32 s83, s83, s37
	v_lshl_add_u64 v[168:169], s[56:57], 0, v[150:151]
	s_mov_b32 m0, s83
	ds_read_b128 v[196:199], v177 offset:16384
	ds_read_b128 v[200:203], v177 offset:17408
	ds_read_b128 v[204:207], v177 offset:18432
	ds_read_b128 v[208:211], v177 offset:19456
	ds_read_b128 v[212:215], v177 offset:20480
	ds_read_b128 v[216:219], v177 offset:21504
	ds_read_b128 v[230:233], v177 offset:22528
	ds_read_b128 v[238:241], v177 offset:23552
	global_load_lds_dwordx4 v[168:169], off
	s_add_i32 m0, s83, 0x2000
	s_add_u32 s84, s56, 0x40000
	v_lshl_add_u64 v[242:243], s[56:57], 0, v[146:147]
	s_addc_u32 s85, s57, 0
	s_add_i32 s0, s0, s37
	global_load_lds_dwordx4 v[242:243], off
	v_lshl_add_u64 v[244:245], s[84:85], 0, v[150:151]
	s_mov_b32 m0, s0
	v_lshl_add_u64 v[246:247], s[58:59], 0, v[148:149]
	global_load_lds_dwordx4 v[244:245], off
	v_lshl_add_u64 v[244:245], s[84:85], 0, v[146:147]
	s_add_i32 m0, s0, 0x2000
	s_nop 0
	global_load_lds_dwordx4 v[244:245], off
	v_lshl_add_u64 v[244:245], s[58:59], 0, v[152:153]
	s_mov_b32 m0, s61
	s_nop 0
	global_load_lds_dwordx4 v[244:245], off
	s_mov_b32 m0, s64
	s_nop 0
	global_load_lds_dwordx4 v[246:247], off
	s_waitcnt vmcnt(8)
	s_waitcnt lgkmcnt(0)
	s_barrier
	s_setprio 1
	s_waitcnt lgkmcnt(0)
	v_mfma_f32_16x16x32_bf16 v[62:65], v[74:77], v[196:199], 0
	v_mfma_f32_16x16x32_bf16 v[54:57], v[90:93], v[196:199], 0
	v_mfma_f32_16x16x32_bf16 v[46:49], v[74:77], v[204:207], 0
	v_mfma_f32_16x16x32_bf16 v[38:41], v[90:93], v[204:207], 0
	v_mfma_f32_16x16x32_bf16 v[30:33], v[74:77], v[212:215], 0
	v_mfma_f32_16x16x32_bf16 v[22:25], v[90:93], v[212:215], 0
	v_mfma_f32_16x16x32_bf16 v[14:17], v[74:77], v[230:233], 0
	v_mfma_f32_16x16x32_bf16 v[6:9], v[90:93], v[230:233], 0
	v_mfma_f32_16x16x32_bf16 v[62:65], v[78:81], v[200:203], v[62:65]
	v_mfma_f32_16x16x32_bf16 v[54:57], v[94:97], v[200:203], v[54:57]
	v_mfma_f32_16x16x32_bf16 v[46:49], v[78:81], v[208:211], v[46:49]
	v_mfma_f32_16x16x32_bf16 v[38:41], v[94:97], v[208:211], v[38:41]
	v_mfma_f32_16x16x32_bf16 v[30:33], v[78:81], v[216:219], v[30:33]
	v_mfma_f32_16x16x32_bf16 v[22:25], v[94:97], v[216:219], v[22:25]
	v_mfma_f32_16x16x32_bf16 v[14:17], v[78:81], v[238:241], v[14:17]
	v_mfma_f32_16x16x32_bf16 v[6:9], v[94:97], v[238:241], v[6:9]
	s_setprio 0
	s_setprio 1
	v_mfma_f32_16x16x32_bf16 v[58:61], v[180:183], v[196:199], 0
	v_mfma_f32_16x16x32_bf16 v[50:53], v[188:191], v[196:199], 0
	v_mfma_f32_16x16x32_bf16 v[42:45], v[180:183], v[204:207], 0
	v_mfma_f32_16x16x32_bf16 v[34:37], v[188:191], v[204:207], 0
	v_mfma_f32_16x16x32_bf16 v[26:29], v[180:183], v[212:215], 0
	v_mfma_f32_16x16x32_bf16 v[18:21], v[188:191], v[212:215], 0
	v_mfma_f32_16x16x32_bf16 v[10:13], v[180:183], v[230:233], 0
	v_mfma_f32_16x16x32_bf16 v[2:5], v[188:191], v[230:233], 0
	v_mfma_f32_16x16x32_bf16 v[58:61], v[184:187], v[200:203], v[58:61]
	v_mfma_f32_16x16x32_bf16 v[50:53], v[192:195], v[200:203], v[50:53]
	v_mfma_f32_16x16x32_bf16 v[42:45], v[184:187], v[208:211], v[42:45]
	v_mfma_f32_16x16x32_bf16 v[34:37], v[192:195], v[208:211], v[34:37]
	v_mfma_f32_16x16x32_bf16 v[26:29], v[184:187], v[216:219], v[26:29]
	v_mfma_f32_16x16x32_bf16 v[18:21], v[192:195], v[216:219], v[18:21]
	v_mfma_f32_16x16x32_bf16 v[10:13], v[184:187], v[238:241], v[10:13]
	v_mfma_f32_16x16x32_bf16 v[2:5], v[192:195], v[238:241], v[2:5]
	s_setprio 0
	s_barrier
	s_add_i32 s0, 0, 0x18000
	s_add_i32 s83, 0, 0x1c000
	v_add_u32_e32 v94, s0, v171
	v_add_u32_e32 v155, s83, v171
	ds_read_b128 v[74:77], v94
	ds_read_b128 v[78:81], v94 offset:1024
	ds_read_b128 v[90:93], v94 offset:2048
	ds_read_b128 v[94:97], v94 offset:3072
	ds_read_b128 v[180:183], v155
	ds_read_b128 v[184:187], v155 offset:1024
	ds_read_b128 v[188:191], v155 offset:2048
	ds_read_b128 v[192:195], v155 offset:3072
	s_add_u32 s58, s58, 0x40000
	s_addc_u32 s59, s59, 0
	s_mov_b32 m0, s65
	v_lshl_add_u64 v[248:249], s[58:59], 0, v[152:153]
	ds_read_b128 v[196:199], v177 offset:32768
	ds_read_b128 v[200:203], v177 offset:33792
	ds_read_b128 v[204:207], v177 offset:34816
	ds_read_b128 v[208:211], v177 offset:35840
	ds_read_b128 v[212:215], v177 offset:36864
	ds_read_b128 v[216:219], v177 offset:37888
	ds_read_b128 v[230:233], v177 offset:38912
	ds_read_b128 v[238:241], v177 offset:39936
	global_load_lds_dwordx4 v[248:249], off
	v_lshl_add_u64 v[248:249], s[58:59], 0, v[148:149]
	s_mov_b32 m0, s66
	s_nop 0
	global_load_lds_dwordx4 v[248:249], off
	s_waitcnt vmcnt(8)
	s_waitcnt lgkmcnt(0)
	s_barrier
	s_setprio 1
	s_waitcnt lgkmcnt(0)
	v_mfma_f32_16x16x32_bf16 v[142:145], v[74:77], v[196:199], v[142:145]
	v_mfma_f32_16x16x32_bf16 v[134:137], v[90:93], v[196:199], v[134:137]
	v_mfma_f32_16x16x32_bf16 v[126:129], v[74:77], v[204:207], v[126:129]
	v_mfma_f32_16x16x32_bf16 v[118:121], v[90:93], v[204:207], v[118:121]
	v_mfma_f32_16x16x32_bf16 v[110:113], v[74:77], v[212:215], v[110:113]
	v_mfma_f32_16x16x32_bf16 v[102:105], v[90:93], v[212:215], v[102:105]
	v_mfma_f32_16x16x32_bf16 v[86:89], v[74:77], v[230:233], v[86:89]
	v_mfma_f32_16x16x32_bf16 v[70:73], v[90:93], v[230:233], v[70:73]
	v_mfma_f32_16x16x32_bf16 v[142:145], v[78:81], v[200:203], v[142:145]
	v_mfma_f32_16x16x32_bf16 v[134:137], v[94:97], v[200:203], v[134:137]
	v_mfma_f32_16x16x32_bf16 v[126:129], v[78:81], v[208:211], v[126:129]
	v_mfma_f32_16x16x32_bf16 v[118:121], v[94:97], v[208:211], v[118:121]
	v_mfma_f32_16x16x32_bf16 v[110:113], v[78:81], v[216:219], v[110:113]
	v_mfma_f32_16x16x32_bf16 v[102:105], v[94:97], v[216:219], v[102:105]
	v_mfma_f32_16x16x32_bf16 v[86:89], v[78:81], v[238:241], v[86:89]
	v_mfma_f32_16x16x32_bf16 v[70:73], v[94:97], v[238:241], v[70:73]
	s_setprio 0
	s_setprio 1
	v_mfma_f32_16x16x32_bf16 v[138:141], v[180:183], v[196:199], v[138:141]
	v_mfma_f32_16x16x32_bf16 v[130:133], v[188:191], v[196:199], v[130:133]
	v_mfma_f32_16x16x32_bf16 v[122:125], v[180:183], v[204:207], v[122:125]
	v_mfma_f32_16x16x32_bf16 v[114:117], v[188:191], v[204:207], v[114:117]
	v_mfma_f32_16x16x32_bf16 v[106:109], v[180:183], v[212:215], v[106:109]
	v_mfma_f32_16x16x32_bf16 v[98:101], v[188:191], v[212:215], v[98:101]
	v_mfma_f32_16x16x32_bf16 v[82:85], v[180:183], v[230:233], v[82:85]
	v_mfma_f32_16x16x32_bf16 v[66:69], v[188:191], v[230:233], v[66:69]
	v_mfma_f32_16x16x32_bf16 v[138:141], v[184:187], v[200:203], v[138:141]
	v_mfma_f32_16x16x32_bf16 v[130:133], v[192:195], v[200:203], v[130:133]
	v_mfma_f32_16x16x32_bf16 v[122:125], v[184:187], v[208:211], v[122:125]
	v_mfma_f32_16x16x32_bf16 v[114:117], v[192:195], v[208:211], v[114:117]
	v_mfma_f32_16x16x32_bf16 v[106:109], v[184:187], v[216:219], v[106:109]
	v_mfma_f32_16x16x32_bf16 v[98:101], v[192:195], v[216:219], v[98:101]
	v_mfma_f32_16x16x32_bf16 v[82:85], v[184:187], v[238:241], v[82:85]
	v_mfma_f32_16x16x32_bf16 v[66:69], v[192:195], v[238:241], v[66:69]
	s_setprio 0
	s_barrier
	s_add_i32 s0, s0, s37
	v_lshl_add_u64 v[168:169], v[168:169], 0, s[76:77]
	s_mov_b32 m0, s0
	ds_read_b128 v[196:199], v177 offset:49152
	ds_read_b128 v[200:203], v177 offset:50176
	ds_read_b128 v[204:207], v177 offset:51200
	ds_read_b128 v[208:211], v177 offset:52224
	ds_read_b128 v[212:215], v177 offset:53248
	ds_read_b128 v[216:219], v177 offset:54272
	ds_read_b128 v[230:233], v177 offset:55296
	ds_read_b128 v[238:241], v177 offset:56320
	global_load_lds_dwordx4 v[168:169], off
	s_add_i32 m0, s0, 0x2000
	s_add_u32 s56, s56, 0x40080
	v_lshl_add_u64 v[168:169], v[242:243], 0, s[76:77]
	s_addc_u32 s57, s57, 0
	s_add_i32 s0, s83, s37
	global_load_lds_dwordx4 v[168:169], off
	v_lshl_add_u64 v[168:169], s[56:57], 0, v[150:151]
	s_mov_b32 m0, s0
	s_nop 0
	global_load_lds_dwordx4 v[168:169], off
	v_lshl_add_u64 v[168:169], s[56:57], 0, v[146:147]
	s_add_i32 m0, s0, 0x2000
	s_nop 0
	global_load_lds_dwordx4 v[168:169], off
	v_lshl_add_u64 v[168:169], v[244:245], 0, s[76:77]
	s_mov_b32 m0, s67
	s_nop 0
	global_load_lds_dwordx4 v[168:169], off
	v_lshl_add_u64 v[168:169], v[246:247], 0, s[76:77]
	s_mov_b32 m0, s68
	s_nop 0
	global_load_lds_dwordx4 v[168:169], off
	s_waitcnt vmcnt(8)
	s_waitcnt lgkmcnt(0)
	s_barrier
	s_setprio 1
	s_waitcnt lgkmcnt(0)
	v_mfma_f32_16x16x32_bf16 v[62:65], v[74:77], v[196:199], v[62:65]
	v_mfma_f32_16x16x32_bf16 v[54:57], v[90:93], v[196:199], v[54:57]
	v_mfma_f32_16x16x32_bf16 v[46:49], v[74:77], v[204:207], v[46:49]
	v_mfma_f32_16x16x32_bf16 v[38:41], v[90:93], v[204:207], v[38:41]
	v_mfma_f32_16x16x32_bf16 v[30:33], v[74:77], v[212:215], v[30:33]
	v_mfma_f32_16x16x32_bf16 v[22:25], v[90:93], v[212:215], v[22:25]
	v_mfma_f32_16x16x32_bf16 v[14:17], v[74:77], v[230:233], v[14:17]
	v_mfma_f32_16x16x32_bf16 v[6:9], v[90:93], v[230:233], v[6:9]
	v_mfma_f32_16x16x32_bf16 v[62:65], v[78:81], v[200:203], v[62:65]
	v_mfma_f32_16x16x32_bf16 v[54:57], v[94:97], v[200:203], v[54:57]
	v_mfma_f32_16x16x32_bf16 v[46:49], v[78:81], v[208:211], v[46:49]
	v_mfma_f32_16x16x32_bf16 v[38:41], v[94:97], v[208:211], v[38:41]
	v_mfma_f32_16x16x32_bf16 v[30:33], v[78:81], v[216:219], v[30:33]
	v_mfma_f32_16x16x32_bf16 v[22:25], v[94:97], v[216:219], v[22:25]
	v_mfma_f32_16x16x32_bf16 v[14:17], v[78:81], v[238:241], v[14:17]
	v_mfma_f32_16x16x32_bf16 v[6:9], v[94:97], v[238:241], v[6:9]
	s_setprio 0
	s_setprio 1
	v_mfma_f32_16x16x32_bf16 v[58:61], v[180:183], v[196:199], v[58:61]
	v_mfma_f32_16x16x32_bf16 v[50:53], v[188:191], v[196:199], v[50:53]
	v_mfma_f32_16x16x32_bf16 v[42:45], v[180:183], v[204:207], v[42:45]
	v_mfma_f32_16x16x32_bf16 v[34:37], v[188:191], v[204:207], v[34:37]
	v_mfma_f32_16x16x32_bf16 v[26:29], v[180:183], v[212:215], v[26:29]
	v_mfma_f32_16x16x32_bf16 v[18:21], v[188:191], v[212:215], v[18:21]
	v_mfma_f32_16x16x32_bf16 v[10:13], v[180:183], v[230:233], v[10:13]
	v_mfma_f32_16x16x32_bf16 v[2:5], v[188:191], v[230:233], v[2:5]
	v_mfma_f32_16x16x32_bf16 v[58:61], v[184:187], v[200:203], v[58:61]
	v_mfma_f32_16x16x32_bf16 v[50:53], v[192:195], v[200:203], v[50:53]
	v_mfma_f32_16x16x32_bf16 v[42:45], v[184:187], v[208:211], v[42:45]
	v_mfma_f32_16x16x32_bf16 v[34:37], v[192:195], v[208:211], v[34:37]
	v_mfma_f32_16x16x32_bf16 v[26:29], v[184:187], v[216:219], v[26:29]
	v_mfma_f32_16x16x32_bf16 v[18:21], v[192:195], v[216:219], v[18:21]
	v_mfma_f32_16x16x32_bf16 v[10:13], v[184:187], v[238:241], v[10:13]
	v_mfma_f32_16x16x32_bf16 v[2:5], v[192:195], v[238:241], v[2:5]
	s_setprio 0
	s_barrier
	s_add_i32 s82, s82, 2
	s_add_u32 s52, s52, 0x100
	s_addc_u32 s53, s53, 0
	s_add_u32 s73, s73, 0x100
	s_addc_u32 s75, s75, 0

.LBB0_282:
	s_ashr_i32 s59, s58, 31
	s_lshl_b64 s[20:21], s[58:59], 19
	s_add_u32 s64, s26, s20
	s_addc_u32 s65, s27, s21
	s_and_b64 s[20:21], s[8:9], exec
	s_cselect_b32 s20, s65, s5
	s_cselect_b32 s21, s64, s4
	s_ashr_i32 s57, s56, 31
	s_lshl_b64 s[36:37], s[56:57], 19
	s_add_u32 s66, s35, s36
	s_addc_u32 s67, s40, s37
	s_and_b64 s[36:37], s[8:9], exec
	s_cselect_b32 s36, s67, s7
	s_cselect_b32 s37, s66, s6
	s_add_u32 s4, s4, 0x40080
	s_addc_u32 s5, s5, 0
	s_add_u32 s46, s6, 0x100
	s_addc_u32 s57, s7, 0
	s_mov_b32 s59, -2
	s_add_u32 s6, s4, 0xfffc0080
	s_addc_u32 s7, s5, -1
	s_add_i32 s82, 0, 0x10000
	s_cmp_eq_u32 s59, 12
	s_cselect_b32 s69, s20, s7
	s_cselect_b32 s68, s21, s6
	s_cselect_b32 s7, s36, s57
	s_cselect_b32 s6, s37, s46
	s_add_i32 s84, 0, 0x14000
	v_add_u32_e32 v142, s82, v202
	v_add_u32_e32 v158, s84, v202
	ds_read_b128 v[130:133], v142
	ds_read_b128 v[134:137], v142 offset:1024
	ds_read_b128 v[138:141], v142 offset:2048
	ds_read_b128 v[142:145], v142 offset:3072
	ds_read_b128 v[146:149], v158
	ds_read_b128 v[150:153], v158 offset:1024
	ds_read_b128 v[154:157], v158 offset:2048
	ds_read_b128 v[158:161], v158 offset:3072
	v_lshl_add_u64 v[218:219], s[4:5], 0, v[182:183]
	s_add_i32 m0, s87, 0xc000
	ds_read_b128 v[186:189], v204
	ds_read_b128 v[190:193], v204 offset:1024
	ds_read_b128 v[194:197], v204 offset:2048
	ds_read_b128 v[198:201], v204 offset:3072
	ds_read_b128 v[206:209], v204 offset:4096
	ds_read_b128 v[210:213], v204 offset:5120
	ds_read_b128 v[214:217], v204 offset:6144
	ds_read_b128 v[238:241], v204 offset:7168
	global_load_lds_dwordx4 v[218:219], off
	v_lshl_add_u64 v[218:219], s[4:5], 0, v[184:185]
	s_add_i32 m0, s87, 0xe000
	s_nop 0
	global_load_lds_dwordx4 v[218:219], off
	s_waitcnt vmcnt(8)
	s_waitcnt lgkmcnt(0)
	s_barrier
	s_setprio 1
	s_waitcnt lgkmcnt(0)
	v_mfma_f32_16x16x32_bf16 v[2:5], v[130:133], v[186:189], 0
	v_mfma_f32_16x16x32_bf16 v[6:9], v[138:141], v[186:189], 0
	v_mfma_f32_16x16x32_bf16 v[30:33], v[130:133], v[194:197], 0
	v_mfma_f32_16x16x32_bf16 v[26:29], v[138:141], v[194:197], 0
	v_mfma_f32_16x16x32_bf16 v[34:37], v[130:133], v[206:209], 0
	v_mfma_f32_16x16x32_bf16 v[42:45], v[138:141], v[206:209], 0
	v_mfma_f32_16x16x32_bf16 v[62:65], v[130:133], v[214:217], 0
	v_mfma_f32_16x16x32_bf16 v[58:61], v[138:141], v[214:217], 0
	v_mfma_f32_16x16x32_bf16 v[2:5], v[134:137], v[190:193], v[2:5]
	v_mfma_f32_16x16x32_bf16 v[6:9], v[142:145], v[190:193], v[6:9]
	v_mfma_f32_16x16x32_bf16 v[30:33], v[134:137], v[198:201], v[30:33]
	v_mfma_f32_16x16x32_bf16 v[26:29], v[142:145], v[198:201], v[26:29]
	v_mfma_f32_16x16x32_bf16 v[34:37], v[134:137], v[210:213], v[34:37]
	v_mfma_f32_16x16x32_bf16 v[42:45], v[142:145], v[210:213], v[42:45]
	v_mfma_f32_16x16x32_bf16 v[62:65], v[134:137], v[238:241], v[62:65]
	v_mfma_f32_16x16x32_bf16 v[58:61], v[142:145], v[238:241], v[58:61]
	s_setprio 0
	s_setprio 1
	v_mfma_f32_16x16x32_bf16 v[14:17], v[146:149], v[186:189], 0
	v_mfma_f32_16x16x32_bf16 v[10:13], v[154:157], v[186:189], 0
	v_mfma_f32_16x16x32_bf16 v[22:25], v[146:149], v[194:197], 0
	v_mfma_f32_16x16x32_bf16 v[18:21], v[154:157], v[194:197], 0
	v_mfma_f32_16x16x32_bf16 v[46:49], v[146:149], v[206:209], 0
	v_mfma_f32_16x16x32_bf16 v[38:41], v[154:157], v[206:209], 0
	v_mfma_f32_16x16x32_bf16 v[54:57], v[146:149], v[214:217], 0
	v_mfma_f32_16x16x32_bf16 v[50:53], v[154:157], v[214:217], 0
	v_mfma_f32_16x16x32_bf16 v[14:17], v[150:153], v[190:193], v[14:17]
	v_mfma_f32_16x16x32_bf16 v[10:13], v[158:161], v[190:193], v[10:13]
	v_mfma_f32_16x16x32_bf16 v[22:25], v[150:153], v[198:201], v[22:25]
	v_mfma_f32_16x16x32_bf16 v[18:21], v[158:161], v[198:201], v[18:21]
	v_mfma_f32_16x16x32_bf16 v[46:49], v[150:153], v[210:213], v[46:49]
	v_mfma_f32_16x16x32_bf16 v[38:41], v[158:161], v[210:213], v[38:41]
	v_mfma_f32_16x16x32_bf16 v[54:57], v[150:153], v[238:241], v[54:57]
	v_mfma_f32_16x16x32_bf16 v[50:53], v[158:161], v[238:241], v[50:53]
	s_setprio 0
	s_barrier
	s_add_i32 s82, s82, s41
	v_lshl_add_u64 v[218:219], s[6:7], 0, v[164:165]
	s_mov_b32 m0, s82
	ds_read_b128 v[186:189], v204 offset:16384
	ds_read_b128 v[190:193], v204 offset:17408
	ds_read_b128 v[194:197], v204 offset:18432
	ds_read_b128 v[198:201], v204 offset:19456
	ds_read_b128 v[206:209], v204 offset:20480
	ds_read_b128 v[210:213], v204 offset:21504
	ds_read_b128 v[214:217], v204 offset:22528
	ds_read_b128 v[238:241], v204 offset:23552
	global_load_lds_dwordx4 v[218:219], off
	s_add_i32 m0, s82, 0x2000
	s_add_u32 s82, s6, 0x40000
	v_lshl_add_u64 v[230:231], s[6:7], 0, v[162:163]
	s_addc_u32 s83, s7, 0
	s_add_i32 s84, s84, s41
	global_load_lds_dwordx4 v[230:231], off
	v_lshl_add_u64 v[232:233], s[82:83], 0, v[164:165]
	s_mov_b32 m0, s84
	v_lshl_add_u64 v[242:243], s[68:69], 0, v[162:163]
	global_load_lds_dwordx4 v[232:233], off
	v_lshl_add_u64 v[232:233], s[82:83], 0, v[162:163]
	s_add_i32 m0, s84, 0x2000
	s_nop 0
	global_load_lds_dwordx4 v[232:233], off
	v_lshl_add_u64 v[232:233], s[68:69], 0, v[164:165]
	s_mov_b32 m0, s87
	s_nop 0
	global_load_lds_dwordx4 v[232:233], off
	s_mov_b32 m0, s75
	s_nop 0
	global_load_lds_dwordx4 v[242:243], off
	s_waitcnt vmcnt(8)
	s_waitcnt lgkmcnt(0)
	s_barrier
	s_setprio 1
	s_waitcnt lgkmcnt(0)
	v_mfma_f32_16x16x32_bf16 v[74:77], v[130:133], v[186:189], 0
	v_mfma_f32_16x16x32_bf16 v[70:73], v[138:141], v[186:189], 0
	v_mfma_f32_16x16x32_bf16 v[94:97], v[130:133], v[194:197], 0
	v_mfma_f32_16x16x32_bf16 v[90:93], v[138:141], v[194:197], 0
	v_mfma_f32_16x16x32_bf16 v[106:109], v[130:133], v[206:209], 0
	v_mfma_f32_16x16x32_bf16 v[102:105], v[138:141], v[206:209], 0
	v_mfma_f32_16x16x32_bf16 v[118:121], v[130:133], v[214:217], 0
	v_mfma_f32_16x16x32_bf16 v[114:117], v[138:141], v[214:217], 0
	v_mfma_f32_16x16x32_bf16 v[74:77], v[134:137], v[190:193], v[74:77]
	v_mfma_f32_16x16x32_bf16 v[70:73], v[142:145], v[190:193], v[70:73]
	v_mfma_f32_16x16x32_bf16 v[94:97], v[134:137], v[198:201], v[94:97]
	v_mfma_f32_16x16x32_bf16 v[90:93], v[142:145], v[198:201], v[90:93]
	v_mfma_f32_16x16x32_bf16 v[106:109], v[134:137], v[210:213], v[106:109]
	v_mfma_f32_16x16x32_bf16 v[102:105], v[142:145], v[210:213], v[102:105]
	v_mfma_f32_16x16x32_bf16 v[118:121], v[134:137], v[238:241], v[118:121]
	v_mfma_f32_16x16x32_bf16 v[114:117], v[142:145], v[238:241], v[114:117]
	s_setprio 0
	s_setprio 1
	v_mfma_f32_16x16x32_bf16 v[78:81], v[146:149], v[186:189], 0
	v_mfma_f32_16x16x32_bf16 v[66:69], v[154:157], v[186:189], 0
	v_mfma_f32_16x16x32_bf16 v[86:89], v[146:149], v[194:197], 0
	v_mfma_f32_16x16x32_bf16 v[82:85], v[154:157], v[194:197], 0
	v_mfma_f32_16x16x32_bf16 v[110:113], v[146:149], v[206:209], 0
	v_mfma_f32_16x16x32_bf16 v[98:101], v[154:157], v[206:209], 0
	v_mfma_f32_16x16x32_bf16 v[122:125], v[146:149], v[214:217], 0
	v_mfma_f32_16x16x32_bf16 v[126:129], v[154:157], v[214:217], 0
	v_mfma_f32_16x16x32_bf16 v[78:81], v[150:153], v[190:193], v[78:81]
	v_mfma_f32_16x16x32_bf16 v[66:69], v[158:161], v[190:193], v[66:69]
	v_mfma_f32_16x16x32_bf16 v[86:89], v[150:153], v[198:201], v[86:89]
	v_mfma_f32_16x16x32_bf16 v[82:85], v[158:161], v[198:201], v[82:85]
	v_mfma_f32_16x16x32_bf16 v[110:113], v[150:153], v[210:213], v[110:113]
	v_mfma_f32_16x16x32_bf16 v[98:101], v[158:161], v[210:213], v[98:101]
	v_mfma_f32_16x16x32_bf16 v[122:125], v[150:153], v[238:241], v[122:125]
	v_mfma_f32_16x16x32_bf16 v[126:129], v[158:161], v[238:241], v[126:129]
	s_setprio 0
	s_barrier
	s_add_i32 s82, 0, 0x18000
	s_add_i32 s83, 0, 0x1c000
	v_add_u32_e32 v142, s82, v202
	v_add_u32_e32 v158, s83, v202
	ds_read_b128 v[130:133], v142
	ds_read_b128 v[134:137], v142 offset:1024
	ds_read_b128 v[138:141], v142 offset:2048
	ds_read_b128 v[142:145], v142 offset:3072
	ds_read_b128 v[146:149], v158
	ds_read_b128 v[150:153], v158 offset:1024
	ds_read_b128 v[154:157], v158 offset:2048
	ds_read_b128 v[158:161], v158 offset:3072
	s_add_u32 s68, s68, 0x40000
	s_addc_u32 s69, s69, 0
	s_mov_b32 m0, s72
	v_lshl_add_u64 v[244:245], s[68:69], 0, v[164:165]
	ds_read_b128 v[186:189], v204 offset:32768
	ds_read_b128 v[190:193], v204 offset:33792
	ds_read_b128 v[194:197], v204 offset:34816
	ds_read_b128 v[198:201], v204 offset:35840
	ds_read_b128 v[206:209], v204 offset:36864
	ds_read_b128 v[210:213], v204 offset:37888
	ds_read_b128 v[214:217], v204 offset:38912
	ds_read_b128 v[238:241], v204 offset:39936
	global_load_lds_dwordx4 v[244:245], off
	v_lshl_add_u64 v[244:245], s[68:69], 0, v[162:163]
	s_mov_b32 m0, s73
	s_nop 0
	global_load_lds_dwordx4 v[244:245], off
	s_waitcnt vmcnt(8)
	s_waitcnt lgkmcnt(0)
	s_barrier
	s_setprio 1
	s_waitcnt lgkmcnt(0)
	v_mfma_f32_16x16x32_bf16 v[2:5], v[130:133], v[186:189], v[2:5]
	v_mfma_f32_16x16x32_bf16 v[6:9], v[138:141], v[186:189], v[6:9]
	v_mfma_f32_16x16x32_bf16 v[30:33], v[130:133], v[194:197], v[30:33]
	v_mfma_f32_16x16x32_bf16 v[26:29], v[138:141], v[194:197], v[26:29]
	v_mfma_f32_16x16x32_bf16 v[34:37], v[130:133], v[206:209], v[34:37]
	v_mfma_f32_16x16x32_bf16 v[42:45], v[138:141], v[206:209], v[42:45]
	v_mfma_f32_16x16x32_bf16 v[62:65], v[130:133], v[214:217], v[62:65]
	v_mfma_f32_16x16x32_bf16 v[58:61], v[138:141], v[214:217], v[58:61]
	v_mfma_f32_16x16x32_bf16 v[2:5], v[134:137], v[190:193], v[2:5]
	v_mfma_f32_16x16x32_bf16 v[6:9], v[142:145], v[190:193], v[6:9]
	v_mfma_f32_16x16x32_bf16 v[30:33], v[134:137], v[198:201], v[30:33]
	v_mfma_f32_16x16x32_bf16 v[26:29], v[142:145], v[198:201], v[26:29]
	v_mfma_f32_16x16x32_bf16 v[34:37], v[134:137], v[210:213], v[34:37]
	v_mfma_f32_16x16x32_bf16 v[42:45], v[142:145], v[210:213], v[42:45]
	v_mfma_f32_16x16x32_bf16 v[62:65], v[134:137], v[238:241], v[62:65]
	v_mfma_f32_16x16x32_bf16 v[58:61], v[142:145], v[238:241], v[58:61]
	s_setprio 0
	s_setprio 1
	v_mfma_f32_16x16x32_bf16 v[14:17], v[146:149], v[186:189], v[14:17]
	v_mfma_f32_16x16x32_bf16 v[10:13], v[154:157], v[186:189], v[10:13]
	v_mfma_f32_16x16x32_bf16 v[22:25], v[146:149], v[194:197], v[22:25]
	v_mfma_f32_16x16x32_bf16 v[18:21], v[154:157], v[194:197], v[18:21]
	v_mfma_f32_16x16x32_bf16 v[46:49], v[146:149], v[206:209], v[46:49]
	v_mfma_f32_16x16x32_bf16 v[38:41], v[154:157], v[206:209], v[38:41]
	v_mfma_f32_16x16x32_bf16 v[54:57], v[146:149], v[214:217], v[54:57]
	v_mfma_f32_16x16x32_bf16 v[50:53], v[154:157], v[214:217], v[50:53]
	v_mfma_f32_16x16x32_bf16 v[14:17], v[150:153], v[190:193], v[14:17]
	v_mfma_f32_16x16x32_bf16 v[10:13], v[158:161], v[190:193], v[10:13]
	v_mfma_f32_16x16x32_bf16 v[22:25], v[150:153], v[198:201], v[22:25]
	v_mfma_f32_16x16x32_bf16 v[18:21], v[158:161], v[198:201], v[18:21]
	v_mfma_f32_16x16x32_bf16 v[46:49], v[150:153], v[210:213], v[46:49]
	v_mfma_f32_16x16x32_bf16 v[38:41], v[158:161], v[210:213], v[38:41]
	v_mfma_f32_16x16x32_bf16 v[54:57], v[150:153], v[238:241], v[54:57]
	v_mfma_f32_16x16x32_bf16 v[50:53], v[158:161], v[238:241], v[50:53]
	s_setprio 0
	s_barrier
	s_add_i32 s68, s82, s41
	v_lshl_add_u64 v[218:219], v[218:219], 0, s[76:77]
	s_mov_b32 m0, s68
	ds_read_b128 v[186:189], v204 offset:49152
	ds_read_b128 v[190:193], v204 offset:50176
	ds_read_b128 v[194:197], v204 offset:51200
	ds_read_b128 v[198:201], v204 offset:52224
	ds_read_b128 v[206:209], v204 offset:53248
	ds_read_b128 v[210:213], v204 offset:54272
	ds_read_b128 v[214:217], v204 offset:55296
	ds_read_b128 v[238:241], v204 offset:56320
	global_load_lds_dwordx4 v[218:219], off
	s_add_i32 m0, s68, 0x2000
	s_add_u32 s6, s6, 0x40080
	v_lshl_add_u64 v[218:219], v[230:231], 0, s[76:77]
	s_addc_u32 s7, s7, 0
	s_add_i32 s68, s83, s41
	global_load_lds_dwordx4 v[218:219], off
	v_lshl_add_u64 v[218:219], s[6:7], 0, v[164:165]
	s_mov_b32 m0, s68
	s_nop 0
	global_load_lds_dwordx4 v[218:219], off
	v_lshl_add_u64 v[218:219], s[6:7], 0, v[162:163]
	s_add_i32 m0, s68, 0x2000
	s_nop 0
	global_load_lds_dwordx4 v[218:219], off
	v_lshl_add_u64 v[218:219], v[232:233], 0, s[76:77]
	s_mov_b32 m0, s34
	s_nop 0
	global_load_lds_dwordx4 v[218:219], off
	v_lshl_add_u64 v[218:219], v[242:243], 0, s[76:77]
	s_mov_b32 m0, s30
	s_nop 0
	global_load_lds_dwordx4 v[218:219], off
	s_waitcnt vmcnt(8)
	s_waitcnt lgkmcnt(0)
	s_barrier
	s_setprio 1
	s_waitcnt lgkmcnt(0)
	v_mfma_f32_16x16x32_bf16 v[74:77], v[130:133], v[186:189], v[74:77]
	v_mfma_f32_16x16x32_bf16 v[70:73], v[138:141], v[186:189], v[70:73]
	v_mfma_f32_16x16x32_bf16 v[94:97], v[130:133], v[194:197], v[94:97]
	v_mfma_f32_16x16x32_bf16 v[90:93], v[138:141], v[194:197], v[90:93]
	v_mfma_f32_16x16x32_bf16 v[106:109], v[130:133], v[206:209], v[106:109]
	v_mfma_f32_16x16x32_bf16 v[102:105], v[138:141], v[206:209], v[102:105]
	v_mfma_f32_16x16x32_bf16 v[118:121], v[130:133], v[214:217], v[118:121]
	v_mfma_f32_16x16x32_bf16 v[114:117], v[138:141], v[214:217], v[114:117]
	v_mfma_f32_16x16x32_bf16 v[74:77], v[134:137], v[190:193], v[74:77]
	v_mfma_f32_16x16x32_bf16 v[70:73], v[142:145], v[190:193], v[70:73]
	v_mfma_f32_16x16x32_bf16 v[94:97], v[134:137], v[198:201], v[94:97]
	v_mfma_f32_16x16x32_bf16 v[90:93], v[142:145], v[198:201], v[90:93]
	v_mfma_f32_16x16x32_bf16 v[106:109], v[134:137], v[210:213], v[106:109]
	v_mfma_f32_16x16x32_bf16 v[102:105], v[142:145], v[210:213], v[102:105]
	v_mfma_f32_16x16x32_bf16 v[118:121], v[134:137], v[238:241], v[118:121]
	v_mfma_f32_16x16x32_bf16 v[114:117], v[142:145], v[238:241], v[114:117]
	s_setprio 0
	s_setprio 1
	v_mfma_f32_16x16x32_bf16 v[78:81], v[146:149], v[186:189], v[78:81]
	v_mfma_f32_16x16x32_bf16 v[66:69], v[154:157], v[186:189], v[66:69]
	v_mfma_f32_16x16x32_bf16 v[86:89], v[146:149], v[194:197], v[86:89]
	v_mfma_f32_16x16x32_bf16 v[82:85], v[154:157], v[194:197], v[82:85]
	v_mfma_f32_16x16x32_bf16 v[110:113], v[146:149], v[206:209], v[110:113]
	v_mfma_f32_16x16x32_bf16 v[98:101], v[154:157], v[206:209], v[98:101]
	v_mfma_f32_16x16x32_bf16 v[122:125], v[146:149], v[214:217], v[122:125]
	v_mfma_f32_16x16x32_bf16 v[126:129], v[154:157], v[214:217], v[126:129]
	v_mfma_f32_16x16x32_bf16 v[78:81], v[150:153], v[190:193], v[78:81]
	v_mfma_f32_16x16x32_bf16 v[66:69], v[158:161], v[190:193], v[66:69]
	v_mfma_f32_16x16x32_bf16 v[86:89], v[150:153], v[198:201], v[86:89]
	v_mfma_f32_16x16x32_bf16 v[82:85], v[158:161], v[198:201], v[82:85]
	v_mfma_f32_16x16x32_bf16 v[110:113], v[150:153], v[210:213], v[110:113]
	v_mfma_f32_16x16x32_bf16 v[98:101], v[158:161], v[210:213], v[98:101]
	v_mfma_f32_16x16x32_bf16 v[122:125], v[150:153], v[238:241], v[122:125]
	v_mfma_f32_16x16x32_bf16 v[126:129], v[158:161], v[238:241], v[126:129]
	s_setprio 0
	s_barrier
	s_add_i32 s59, s59, 2
	s_add_u32 s4, s4, 0x100
	s_addc_u32 s5, s5, 0
	s_add_u32 s46, s46, 0x100
	s_addc_u32 s57, s57, 0

.LBB0_670:
	s_add_u32 s6, s58, 0x80
	s_addc_u32 s7, s59, 0
	s_add_u32 s21, s56, 0x100
	s_addc_u32 s26, s57, 0
	s_mov_b32 s27, 0
	s_add_i32 s46, s27, 2
	s_add_u32 s0, s6, 0x80
	s_addc_u32 s56, s7, 0
	s_add_i32 vcc_lo, 0, 0x10000
	s_cmp_eq_u32 s72, s27
	s_cselect_b32 s57, s51, s56
	s_cselect_b32 s56, s50, s0
	s_cselect_b32 s59, s53, s26
	s_cselect_b32 s58, s52, s21
	s_add_i32 s0, 0, 0x14000
	v_add_u32_e32 v70, vcc_lo, v237
	v_add_u32_e32 v94, s0, v237
	ds_read_b128 v[58:61], v70
	ds_read_b128 v[62:65], v70 offset:1024
	ds_read_b128 v[66:69], v70 offset:2048
	ds_read_b128 v[70:73], v70 offset:3072
	ds_read_b128 v[82:85], v94
	ds_read_b128 v[86:89], v94 offset:1024
	ds_read_b128 v[90:93], v94 offset:2048
	ds_read_b128 v[94:97], v94 offset:3072
	v_lshl_add_u64 v[210:211], s[6:7], 0, v[194:195]
	s_add_i32 m0, s64, 0xc000
	ds_read_b128 v[162:165], v239
	ds_read_b128 v[166:169], v239 offset:1024
	ds_read_b128 v[170:173], v239 offset:2048
	ds_read_b128 v[174:177], v239 offset:3072
	ds_read_b128 v[178:181], v239 offset:4096
	ds_read_b128 v[198:201], v239 offset:5120
	ds_read_b128 v[202:205], v239 offset:6144
	ds_read_b128 v[206:209], v239 offset:7168
	global_load_lds_dwordx4 v[210:211], off
	v_lshl_add_u64 v[210:211], s[6:7], 0, v[196:197]
	s_add_i32 m0, s64, 0xe000
	s_nop 0
	global_load_lds_dwordx4 v[210:211], off
	s_waitcnt vmcnt(8)
	s_waitcnt lgkmcnt(0)
	s_barrier
	s_setprio 1
	s_waitcnt lgkmcnt(0)
	v_mfma_f32_16x16x32_bf16 v[158:161], v[58:61], v[162:165], 0
	v_mfma_f32_16x16x32_bf16 v[154:157], v[66:69], v[162:165], 0
	v_mfma_f32_16x16x32_bf16 v[142:145], v[58:61], v[170:173], 0
	v_mfma_f32_16x16x32_bf16 v[138:141], v[66:69], v[170:173], 0
	v_mfma_f32_16x16x32_bf16 v[126:129], v[58:61], v[178:181], 0
	v_mfma_f32_16x16x32_bf16 v[122:125], v[66:69], v[178:181], 0
	v_mfma_f32_16x16x32_bf16 v[110:113], v[58:61], v[202:205], 0
	v_mfma_f32_16x16x32_bf16 v[106:109], v[66:69], v[202:205], 0
	v_mfma_f32_16x16x32_bf16 v[158:161], v[62:65], v[166:169], v[158:161]
	v_mfma_f32_16x16x32_bf16 v[154:157], v[70:73], v[166:169], v[154:157]
	v_mfma_f32_16x16x32_bf16 v[142:145], v[62:65], v[174:177], v[142:145]
	v_mfma_f32_16x16x32_bf16 v[138:141], v[70:73], v[174:177], v[138:141]
	v_mfma_f32_16x16x32_bf16 v[126:129], v[62:65], v[198:201], v[126:129]
	v_mfma_f32_16x16x32_bf16 v[122:125], v[70:73], v[198:201], v[122:125]
	v_mfma_f32_16x16x32_bf16 v[110:113], v[62:65], v[206:209], v[110:113]
	v_mfma_f32_16x16x32_bf16 v[106:109], v[70:73], v[206:209], v[106:109]
	s_setprio 0
	s_setprio 1
	v_mfma_f32_16x16x32_bf16 v[150:153], v[82:85], v[162:165], 0
	v_mfma_f32_16x16x32_bf16 v[146:149], v[90:93], v[162:165], 0
	v_mfma_f32_16x16x32_bf16 v[134:137], v[82:85], v[170:173], 0
	v_mfma_f32_16x16x32_bf16 v[130:133], v[90:93], v[170:173], 0
	v_mfma_f32_16x16x32_bf16 v[118:121], v[82:85], v[178:181], 0
	v_mfma_f32_16x16x32_bf16 v[114:117], v[90:93], v[178:181], 0
	v_mfma_f32_16x16x32_bf16 v[102:105], v[82:85], v[202:205], 0
	v_mfma_f32_16x16x32_bf16 v[98:101], v[90:93], v[202:205], 0
	v_mfma_f32_16x16x32_bf16 v[150:153], v[86:89], v[166:169], v[150:153]
	v_mfma_f32_16x16x32_bf16 v[146:149], v[94:97], v[166:169], v[146:149]
	v_mfma_f32_16x16x32_bf16 v[134:137], v[86:89], v[174:177], v[134:137]
	v_mfma_f32_16x16x32_bf16 v[130:133], v[94:97], v[174:177], v[130:133]
	v_mfma_f32_16x16x32_bf16 v[118:121], v[86:89], v[198:201], v[118:121]
	v_mfma_f32_16x16x32_bf16 v[114:117], v[94:97], v[198:201], v[114:117]
	v_mfma_f32_16x16x32_bf16 v[102:105], v[86:89], v[206:209], v[102:105]
	v_mfma_f32_16x16x32_bf16 v[98:101], v[94:97], v[206:209], v[98:101]
	s_setprio 0
	s_barrier
	s_add_i32 s27, vcc_lo, s61
	v_lshl_add_u64 v[210:211], s[58:59], 0, v[186:187]
	s_mov_b32 m0, s27
	ds_read_b128 v[162:165], v239 offset:16384
	ds_read_b128 v[166:169], v239 offset:17408
	ds_read_b128 v[170:173], v239 offset:18432
	ds_read_b128 v[174:177], v239 offset:19456
	ds_read_b128 v[178:181], v239 offset:20480
	ds_read_b128 v[198:201], v239 offset:21504
	ds_read_b128 v[202:205], v239 offset:22528
	ds_read_b128 v[206:209], v239 offset:23552
	global_load_lds_dwordx4 v[210:211], off
	s_add_i32 m0, s27, 0x2000
	v_lshl_add_u64 v[212:213], s[58:59], 0, v[182:183]
	s_add_u32 s58, s58, s12
	s_addc_u32 s59, s59, 0
	s_add_i32 s0, s0, s61
	global_load_lds_dwordx4 v[212:213], off
	v_lshl_add_u64 v[214:215], s[58:59], 0, v[186:187]
	s_mov_b32 m0, s0
	v_lshl_add_u64 v[216:217], s[58:59], 0, v[182:183]
	global_load_lds_dwordx4 v[214:215], off
	s_add_i32 m0, s0, 0x2000
	v_lshl_add_u64 v[218:219], s[56:57], 0, v[188:189]
	global_load_lds_dwordx4 v[216:217], off
	s_mov_b32 m0, s64
	v_lshl_add_u64 v[230:231], s[56:57], 0, v[184:185]
	global_load_lds_dwordx4 v[218:219], off
	s_mov_b32 m0, s65
	s_nop 0
	global_load_lds_dwordx4 v[230:231], off
	s_waitcnt vmcnt(8)
	s_waitcnt lgkmcnt(0)
	s_barrier
	s_setprio 1
	s_waitcnt lgkmcnt(0)
	v_mfma_f32_16x16x32_bf16 v[78:81], v[58:61], v[162:165], 0
	v_mfma_f32_16x16x32_bf16 v[74:77], v[66:69], v[162:165], 0
	v_mfma_f32_16x16x32_bf16 v[46:49], v[58:61], v[170:173], 0
	v_mfma_f32_16x16x32_bf16 v[42:45], v[66:69], v[170:173], 0
	v_mfma_f32_16x16x32_bf16 v[30:33], v[58:61], v[178:181], 0
	v_mfma_f32_16x16x32_bf16 v[26:29], v[66:69], v[178:181], 0
	v_mfma_f32_16x16x32_bf16 v[14:17], v[58:61], v[202:205], 0
	v_mfma_f32_16x16x32_bf16 v[10:13], v[66:69], v[202:205], 0
	v_mfma_f32_16x16x32_bf16 v[78:81], v[62:65], v[166:169], v[78:81]
	v_mfma_f32_16x16x32_bf16 v[74:77], v[70:73], v[166:169], v[74:77]
	v_mfma_f32_16x16x32_bf16 v[46:49], v[62:65], v[174:177], v[46:49]
	v_mfma_f32_16x16x32_bf16 v[42:45], v[70:73], v[174:177], v[42:45]
	v_mfma_f32_16x16x32_bf16 v[30:33], v[62:65], v[198:201], v[30:33]
	v_mfma_f32_16x16x32_bf16 v[26:29], v[70:73], v[198:201], v[26:29]
	v_mfma_f32_16x16x32_bf16 v[14:17], v[62:65], v[206:209], v[14:17]
	v_mfma_f32_16x16x32_bf16 v[10:13], v[70:73], v[206:209], v[10:13]
	s_setprio 0
	s_setprio 1
	v_mfma_f32_16x16x32_bf16 v[54:57], v[82:85], v[162:165], 0
	v_mfma_f32_16x16x32_bf16 v[50:53], v[90:93], v[162:165], 0
	v_mfma_f32_16x16x32_bf16 v[38:41], v[82:85], v[170:173], 0
	v_mfma_f32_16x16x32_bf16 v[34:37], v[90:93], v[170:173], 0
	v_mfma_f32_16x16x32_bf16 v[22:25], v[82:85], v[178:181], 0
	v_mfma_f32_16x16x32_bf16 v[18:21], v[90:93], v[178:181], 0
	v_mfma_f32_16x16x32_bf16 v[6:9], v[82:85], v[202:205], 0
	v_mfma_f32_16x16x32_bf16 v[2:5], v[90:93], v[202:205], 0
	v_mfma_f32_16x16x32_bf16 v[54:57], v[86:89], v[166:169], v[54:57]
	v_mfma_f32_16x16x32_bf16 v[50:53], v[94:97], v[166:169], v[50:53]
	v_mfma_f32_16x16x32_bf16 v[38:41], v[86:89], v[174:177], v[38:41]
	v_mfma_f32_16x16x32_bf16 v[34:37], v[94:97], v[174:177], v[34:37]
	v_mfma_f32_16x16x32_bf16 v[22:25], v[86:89], v[198:201], v[22:25]
	v_mfma_f32_16x16x32_bf16 v[18:21], v[94:97], v[198:201], v[18:21]
	v_mfma_f32_16x16x32_bf16 v[6:9], v[86:89], v[206:209], v[6:9]
	v_mfma_f32_16x16x32_bf16 v[2:5], v[94:97], v[206:209], v[2:5]
	s_setprio 0
	s_barrier
	s_add_i32 s0, 0, 0x18000
	s_add_i32 s27, 0, 0x1c000
	v_add_u32_e32 v70, s0, v237
	v_add_u32_e32 v94, s27, v237
	ds_read_b128 v[58:61], v70
	ds_read_b128 v[62:65], v70 offset:1024
	ds_read_b128 v[66:69], v70 offset:2048
	ds_read_b128 v[70:73], v70 offset:3072
	ds_read_b128 v[82:85], v94
	ds_read_b128 v[86:89], v94 offset:1024
	ds_read_b128 v[90:93], v94 offset:2048
	ds_read_b128 v[94:97], v94 offset:3072
	s_add_u32 s56, s56, s12
	s_addc_u32 s57, s57, 0
	s_mov_b32 m0, s66
	v_lshl_add_u64 v[232:233], s[56:57], 0, v[188:189]
	ds_read_b128 v[162:165], v239 offset:32768
	ds_read_b128 v[166:169], v239 offset:33792
	ds_read_b128 v[170:173], v239 offset:34816
	ds_read_b128 v[174:177], v239 offset:35840
	ds_read_b128 v[178:181], v239 offset:36864
	ds_read_b128 v[198:201], v239 offset:37888
	ds_read_b128 v[202:205], v239 offset:38912
	ds_read_b128 v[206:209], v239 offset:39936
	global_load_lds_dwordx4 v[232:233], off
	v_lshl_add_u64 v[232:233], s[56:57], 0, v[184:185]
	s_mov_b32 m0, s67
	s_nop 0
	global_load_lds_dwordx4 v[232:233], off
	s_waitcnt vmcnt(8)
	s_waitcnt lgkmcnt(0)
	s_barrier
	s_setprio 1
	s_waitcnt lgkmcnt(0)
	v_mfma_f32_16x16x32_bf16 v[158:161], v[58:61], v[162:165], v[158:161]
	v_mfma_f32_16x16x32_bf16 v[154:157], v[66:69], v[162:165], v[154:157]
	v_mfma_f32_16x16x32_bf16 v[142:145], v[58:61], v[170:173], v[142:145]
	v_mfma_f32_16x16x32_bf16 v[138:141], v[66:69], v[170:173], v[138:141]
	v_mfma_f32_16x16x32_bf16 v[126:129], v[58:61], v[178:181], v[126:129]
	v_mfma_f32_16x16x32_bf16 v[122:125], v[66:69], v[178:181], v[122:125]
	v_mfma_f32_16x16x32_bf16 v[110:113], v[58:61], v[202:205], v[110:113]
	v_mfma_f32_16x16x32_bf16 v[106:109], v[66:69], v[202:205], v[106:109]
	v_mfma_f32_16x16x32_bf16 v[158:161], v[62:65], v[166:169], v[158:161]
	v_mfma_f32_16x16x32_bf16 v[154:157], v[70:73], v[166:169], v[154:157]
	v_mfma_f32_16x16x32_bf16 v[142:145], v[62:65], v[174:177], v[142:145]
	v_mfma_f32_16x16x32_bf16 v[138:141], v[70:73], v[174:177], v[138:141]
	v_mfma_f32_16x16x32_bf16 v[126:129], v[62:65], v[198:201], v[126:129]
	v_mfma_f32_16x16x32_bf16 v[122:125], v[70:73], v[198:201], v[122:125]
	v_mfma_f32_16x16x32_bf16 v[110:113], v[62:65], v[206:209], v[110:113]
	v_mfma_f32_16x16x32_bf16 v[106:109], v[70:73], v[206:209], v[106:109]
	s_setprio 0
	s_setprio 1
	v_mfma_f32_16x16x32_bf16 v[150:153], v[82:85], v[162:165], v[150:153]
	v_mfma_f32_16x16x32_bf16 v[146:149], v[90:93], v[162:165], v[146:149]
	v_mfma_f32_16x16x32_bf16 v[134:137], v[82:85], v[170:173], v[134:137]
	v_mfma_f32_16x16x32_bf16 v[130:133], v[90:93], v[170:173], v[130:133]
	v_mfma_f32_16x16x32_bf16 v[118:121], v[82:85], v[178:181], v[118:121]
	v_mfma_f32_16x16x32_bf16 v[114:117], v[90:93], v[178:181], v[114:117]
	v_mfma_f32_16x16x32_bf16 v[102:105], v[82:85], v[202:205], v[102:105]
	v_mfma_f32_16x16x32_bf16 v[98:101], v[90:93], v[202:205], v[98:101]
	v_mfma_f32_16x16x32_bf16 v[150:153], v[86:89], v[166:169], v[150:153]
	v_mfma_f32_16x16x32_bf16 v[146:149], v[94:97], v[166:169], v[146:149]
	v_mfma_f32_16x16x32_bf16 v[134:137], v[86:89], v[174:177], v[134:137]
	v_mfma_f32_16x16x32_bf16 v[130:133], v[94:97], v[174:177], v[130:133]
	v_mfma_f32_16x16x32_bf16 v[118:121], v[86:89], v[198:201], v[118:121]
	v_mfma_f32_16x16x32_bf16 v[114:117], v[94:97], v[198:201], v[114:117]
	v_mfma_f32_16x16x32_bf16 v[102:105], v[86:89], v[206:209], v[102:105]
	v_mfma_f32_16x16x32_bf16 v[98:101], v[94:97], v[206:209], v[98:101]
	s_setprio 0
	s_barrier
	s_add_i32 s0, s0, s61
	v_lshl_add_u64 v[210:211], v[210:211], 0, s[76:77]
	s_mov_b32 m0, s0
	ds_read_b128 v[162:165], v239 offset:49152
	ds_read_b128 v[166:169], v239 offset:50176
	ds_read_b128 v[170:173], v239 offset:51200
	ds_read_b128 v[174:177], v239 offset:52224
	ds_read_b128 v[178:181], v239 offset:53248
	ds_read_b128 v[198:201], v239 offset:54272
	ds_read_b128 v[202:205], v239 offset:55296
	ds_read_b128 v[206:209], v239 offset:56320
	global_load_lds_dwordx4 v[210:211], off
	v_lshl_add_u64 v[210:211], v[212:213], 0, s[76:77]
	s_add_i32 m0, s0, 0x2000
	s_add_i32 s0, s27, s61
	global_load_lds_dwordx4 v[210:211], off
	v_lshl_add_u64 v[210:211], v[214:215], 0, s[76:77]
	s_mov_b32 m0, s0
	s_nop 0
	global_load_lds_dwordx4 v[210:211], off
	v_lshl_add_u64 v[210:211], v[216:217], 0, s[76:77]
	s_add_i32 m0, s0, 0x2000
	s_nop 0
	global_load_lds_dwordx4 v[210:211], off
	v_lshl_add_u64 v[210:211], v[218:219], 0, s[76:77]
	s_mov_b32 m0, s68
	s_nop 0
	global_load_lds_dwordx4 v[210:211], off
	v_lshl_add_u64 v[210:211], v[230:231], 0, s[76:77]
	s_mov_b32 m0, s69
	s_nop 0
	global_load_lds_dwordx4 v[210:211], off
	s_waitcnt vmcnt(8)
	s_waitcnt lgkmcnt(0)
	s_barrier
	s_setprio 1
	s_waitcnt lgkmcnt(0)
	v_mfma_f32_16x16x32_bf16 v[78:81], v[58:61], v[162:165], v[78:81]
	v_mfma_f32_16x16x32_bf16 v[74:77], v[66:69], v[162:165], v[74:77]
	v_mfma_f32_16x16x32_bf16 v[46:49], v[58:61], v[170:173], v[46:49]
	v_mfma_f32_16x16x32_bf16 v[42:45], v[66:69], v[170:173], v[42:45]
	v_mfma_f32_16x16x32_bf16 v[30:33], v[58:61], v[178:181], v[30:33]
	v_mfma_f32_16x16x32_bf16 v[26:29], v[66:69], v[178:181], v[26:29]
	v_mfma_f32_16x16x32_bf16 v[14:17], v[58:61], v[202:205], v[14:17]
	v_mfma_f32_16x16x32_bf16 v[10:13], v[66:69], v[202:205], v[10:13]
	v_mfma_f32_16x16x32_bf16 v[78:81], v[62:65], v[166:169], v[78:81]
	v_mfma_f32_16x16x32_bf16 v[74:77], v[70:73], v[166:169], v[74:77]
	v_mfma_f32_16x16x32_bf16 v[46:49], v[62:65], v[174:177], v[46:49]
	v_mfma_f32_16x16x32_bf16 v[42:45], v[70:73], v[174:177], v[42:45]
	v_mfma_f32_16x16x32_bf16 v[30:33], v[62:65], v[198:201], v[30:33]
	v_mfma_f32_16x16x32_bf16 v[26:29], v[70:73], v[198:201], v[26:29]
	v_mfma_f32_16x16x32_bf16 v[14:17], v[62:65], v[206:209], v[14:17]
	v_mfma_f32_16x16x32_bf16 v[10:13], v[70:73], v[206:209], v[10:13]
	s_setprio 0
	s_setprio 1
	v_mfma_f32_16x16x32_bf16 v[54:57], v[82:85], v[162:165], v[54:57]
	v_mfma_f32_16x16x32_bf16 v[50:53], v[90:93], v[162:165], v[50:53]
	v_mfma_f32_16x16x32_bf16 v[38:41], v[82:85], v[170:173], v[38:41]
	v_mfma_f32_16x16x32_bf16 v[34:37], v[90:93], v[170:173], v[34:37]
	v_mfma_f32_16x16x32_bf16 v[22:25], v[82:85], v[178:181], v[22:25]
	v_mfma_f32_16x16x32_bf16 v[18:21], v[90:93], v[178:181], v[18:21]
	v_mfma_f32_16x16x32_bf16 v[6:9], v[82:85], v[202:205], v[6:9]
	v_mfma_f32_16x16x32_bf16 v[2:5], v[90:93], v[202:205], v[2:5]
	v_mfma_f32_16x16x32_bf16 v[54:57], v[86:89], v[166:169], v[54:57]
	v_mfma_f32_16x16x32_bf16 v[50:53], v[94:97], v[166:169], v[50:53]
	v_mfma_f32_16x16x32_bf16 v[38:41], v[86:89], v[174:177], v[38:41]
	v_mfma_f32_16x16x32_bf16 v[34:37], v[94:97], v[174:177], v[34:37]
	v_mfma_f32_16x16x32_bf16 v[22:25], v[86:89], v[198:201], v[22:25]
	v_mfma_f32_16x16x32_bf16 v[18:21], v[94:97], v[198:201], v[18:21]
	v_mfma_f32_16x16x32_bf16 v[6:9], v[86:89], v[206:209], v[6:9]
	v_mfma_f32_16x16x32_bf16 v[2:5], v[94:97], v[206:209], v[2:5]
	s_setprio 0
	s_barrier
	s_add_u32 s6, s6, 0x100
	s_addc_u32 s7, s7, 0
	s_add_u32 s21, s21, 0x100
	s_addc_u32 s26, s26, 0
	s_mov_b32 s27, s46
